# grid barrier: the first workgroup of each XCD to arrive issues an asynchronous buffer_wbl2 so the leader's final L2 write-back has less dirty data on the critical path
# baseline (speedup 1.0000x reference)
; __device__ __forceinline__ unsigned xb_ld(unsigned* p)              { return __hip_atomic_load(p, __ATOMIC_RELAXED, __HIP_MEMORY_SCOPE_AGENT); }
; __device__ __forceinline__ unsigned xb_add(unsigned* p, unsigned v) { return __hip_atomic_fetch_add(p, v, __ATOMIC_RELAXED, __HIP_MEMORY_SCOPE_AGENT); }
; #define XB_SPIN(cond, bar) do { unsigned _sp = 0; while (cond) { __builtin_amdgcn_s_sleep(1); \
;     if ((++_sp & 255u) == 0u) { if (xb_ld(&(bar)[XB_TMO])) break; if (_sp > XB_SPIN_CAP) { atomicAdd(&(bar)[XB_TMO], 1u); break; } } } } while (0)
; __device__ __forceinline__ void xcd_barrier(const XcdBarrier& b) {
;     ...
;         const unsigned old = xb_add(&bar[XB_XSUB(b.x)], 1u);
;         const unsigned gen = old / nloc;
;         if (old + 1u == (gen + 1u) * nloc) {
;             __builtin_amdgcn_fence(__ATOMIC_RELEASE, "agent");
;             asm volatile("s_waitcnt vmcnt(0)" ::: "memory");
;             const unsigned og = xb_add(&bar[XB_TOP], 1u);
;             const unsigned tg = og / nx;
;             if (og + 1u == (tg + 1u) * nx) xb_add(&bar[XB_TOPGEN], 1u);
;             else XB_SPIN(xb_ld(&bar[XB_TOPGEN]) == tg, bar);
;             __builtin_amdgcn_fence(__ATOMIC_ACQUIRE, "agent");
;             xb_add(&bar[XB_XGEN(b.x)], 1u);
;             asm volatile("s_waitcnt vmcnt(0)" ::: "memory");
;         } else {
;             XB_SPIN(xb_ld(&bar[XB_XGEN(b.x)]) == gen, bar);
.LBB0_531:
	s_or_b64 exec, exec, s[10:11]
	v_cvt_f32_u32_e32 v5, v3
	s_waitcnt vmcnt(0)
	v_readfirstlane_b32 s4, v4
	v_sub_u32_e32 v4, 0, v3
	v_rcp_iflag_f32_e32 v5, v5
	v_add_u32_e32 v6, s4, v1
	v_mul_f32_e32 v5, 0x4f7ffffe, v5
	v_cvt_u32_f32_e32 v5, v5
	v_mul_lo_u32 v1, v4, v5
	v_mul_hi_u32 v1, v5, v1
	v_add_u32_e32 v1, v5, v1
	v_mul_hi_u32 v1, v6, v1
	v_mul_lo_u32 v4, v1, v3
	v_sub_u32_e32 v4, v6, v4
	v_add_u32_e32 v5, 1, v1
	v_cmp_ge_u32_e32 vcc, v4, v3
	s_nop 1
	v_cndmask_b32_e32 v1, v1, v5, vcc
	v_sub_u32_e32 v5, v4, v3
	v_cndmask_b32_e32 v4, v4, v5, vcc
	v_add_u32_e32 v5, 1, v1
	v_cmp_ge_u32_e32 vcc, v4, v3
	v_add_u32_e32 v4, 1, v6
	s_nop 0
	v_cndmask_b32_e32 v1, v1, v5, vcc
	v_mul_lo_u32 v5, v3, v1
	v_cmp_eq_u32_e32 vcc, v6, v5
	s_nop 4
	s_cbranch_vccz .Lxb_not_first
	buffer_wbl2 sc1
.Lxb_not_first:
	v_add_u32_e32 v3, v5, v3
	v_cmp_ne_u32_e32 vcc, v4, v3
	s_and_saveexec_b64 s[4:5], vcc
	s_xor_b64 s[4:5], exec, s[4:5]
	s_cbranch_execz .LBB0_545
	s_waitcnt lgkmcnt(0)
	v_mov_b32_e32 v2, 0x2000
	global_load_dword v2, v2, s[8:9] offset:1024 sc1
	s_add_u32 s14, s8, 0x2400
	s_addc_u32 s15, s9, 0
	s_waitcnt vmcnt(0)
	v_cmp_eq_u32_e32 vcc, v2, v1
	s_and_saveexec_b64 s[10:11], vcc
	s_cbranch_execz .LBB0_544
	s_add_u32 s12, s70, 0x27000200
	s_addc_u32 s13, s71, 0
	s_mov_b32 s20, 1
	s_mov_b64 s[16:17], 0
	s_branch .LBB0_535
